# P3 queue order: 128 largest FoX units first, then all NSA units, then remaining FoX units in descending cost (small units at the tail) instead of NSA/FoX alternation; same units, same work
# speedup vs baseline: 1.0119x; 1.0013x over previous
; #define LAS __attribute__((address_space(3)))
; DI void fox_unit(const Params& P, lptr L, int u, int tid, int lane, int wid) {
;     ...
;     const int bh = u & 15, b = bh >> 3, h = bh & 7, qt = 63 - (u >> 4);
;     const int i = lane & 31, hi = lane >> 5;
;     const int t0 = qt * 256, tq0 = t0 + wid * 32, t = tq0 + i;
;     const float* carr = CARR + (size_t)(b * 8 + h) * SEQ;
;     volatile LAS int* misc = (volatile LAS int*)(L + AL_MISC);
;     if (tid == 0) misc[0] = t0 >> 6;
;     __syncthreads();
;     {
;         const float qn2 = __uint_as_float(CTL[CW_NRM + b * 16 + h]), kn2 = __uint_as_float(CTL[CW_NRM + b * 16 + 8 + h]);
;         const float bnd = 2.f * sqrtf(qn2 * kn2) * (1.01f / L2E) + 0.5f;
;         const int ntl = t0 >> 6;
;         if (tid < ntl) { if (carr[t0] - carr[64 * tid + 63] + bnd >= -30.f)     __hip_atomic_fetch_min((LAS int*)(L + AL_MISC), tid, __ATOMIC_RELAXED, __HIP_MEMORY_SCOPE_WORKGROUP); }
; __global__ void __launch_bounds__(512) fwd_kernel(Params P) {
;     ...
;                 const int v = u - 128;
;                 if (v & 1) fox_unit(P, L, v >> 1, tid, lane, wid);
.LBB0_472:
	s_or_b64 exec, exec, s[0:1]
	s_waitcnt lgkmcnt(0)
	s_barrier
	ds_read_b32 v0, v1 offset:37632
	v_readlane_b32 s0, v250, 29
	v_readlane_b32 s1, v250, 30
	s_xor_b64 s[24:25], s[0:1], -1
	v_readlane_b32 s0, v251, 57
	s_waitcnt lgkmcnt(0)
	v_readfirstlane_b32 s7, v0
	v_cmp_le_i32_e64 s[20:21], s0, v0
	s_and_b64 vcc, exec, s[20:21]
	s_cbranch_vccnz .LBB0_467
	s_cmpk_lt_i32 s7, 0x880
	s_mov_b64 s[2:3], -1
	s_cbranch_scc0 .LBB0_634
	s_cmpk_gt_i32 s7, 0x7f
	s_cbranch_scc0 .LBB0_626
	s_add_i32 s47, s7, 0xffffff80
	s_cmpk_lt_u32 s47, 0x80
	s_cbranch_scc1 .Lq_remap_fox
	s_cmpk_lt_u32 s47, 0x480
	s_cbranch_scc1 .Lq_remap_nsa
	s_addk_i32 s47, 0xfc00
.Lq_remap_fox:
	s_lshl_b32 s47, s47, 1
	s_or_b32 s47, s47, 1
	s_branch .Lq_remap_done
.Lq_remap_nsa:
	s_addk_i32 s47, 0xff80
	s_lshl_b32 s47, s47, 1
.Lq_remap_done:
	s_add_i32 s7, s47, 0x80
	s_bitcmp0_b32 s7, 0
	s_mov_b64 s[0:1], -1
	s_cbranch_scc1 .LBB0_518
	s_lshr_b32 s0, s47, 5
	s_xor_b32 s3, s0, 63
	s_lshl_b32 s53, s3, 2
	s_mov_b64 s[0:1], exec
	v_readlane_b32 s22, v251, 20
	v_readlane_b32 s23, v251, 21
	s_and_b64 s[22:23], s[0:1], s[22:23]
	s_mov_b64 exec, s[22:23]
	v_mov_b32_e32 v0, s53
	ds_write_b32 v1, v0 offset:37376
	s_or_b64 exec, exec, s[0:1]
	s_lshl_b32 s0, s47, 15
	s_bfe_u32 s2, s7, 0x10004
	s_bfe_u32 s33, s47, 0x30001
	s_lshl_b32 s22, s3, 8
	s_and_b32 s0, s0, 0xf0000
	v_readlane_b32 s1, v251, 62
	s_add_u32 s26, s1, s0
	v_readlane_b32 s0, v251, 63
	s_addc_u32 s27, s0, 0
	v_cmp_gt_u32_e32 vcc, s53, v194
	s_waitcnt lgkmcnt(0)
	s_barrier
	s_and_saveexec_b64 s[28:29], vcc
	s_cbranch_execz .LBB0_484
	s_lshl_b32 s0, s33, 2
	s_lshl_b32 s1, s2, 6
	s_or_b32 s0, s1, s0
	v_mov_b32_e32 v0, s0
	global_load_dword v2, v0, s[34:35] offset:768
	s_mov_b32 s23, s83
	global_load_dword v0, v0, s[34:35] offset:800
	s_lshl_b64 s[0:1], s[22:23], 2
	s_add_u32 s0, s26, s0
	s_addc_u32 s1, s27, s1
	global_load_dword v6, v1, s[0:1]
	global_load_dword v7, v203, s[26:27] offset:252
	s_mov_b32 s0, 0xf800000
	s_waitcnt vmcnt(0)
	v_mul_f32_e32 v0, v2, v0
	v_cmp_gt_f32_e32 vcc, s0, v0
	v_mul_f32_e32 v2, 0x4f800000, v0
	s_nop 0
	v_cndmask_b32_e32 v0, v0, v2, vcc
	v_sqrt_f32_e32 v2, v0
	s_nop 0
	v_add_u32_e32 v3, -1, v2
	v_fma_f32 v4, -v3, v2, v0
	v_cmp_ge_f32_e64 s[0:1], 0, v4
	v_add_u32_e32 v4, 1, v2
	s_nop 0
	v_cndmask_b32_e64 v3, v2, v3, s[0:1]
	v_fma_f32 v2, -v4, v2, v0
	v_cmp_lt_f32_e64 s[0:1], 0, v2
	s_nop 1
	v_cndmask_b32_e64 v2, v3, v4, s[0:1]
	v_mul_f32_e32 v3, 0x37800000, v2
	v_cndmask_b32_e32 v2, v2, v3, vcc
	v_cmp_class_f32_e32 vcc, v0, v202
	s_mov_b32 s0, 0x3f33385b
	s_nop 0
	v_cndmask_b32_e32 v0, v2, v0, vcc
	v_add_f32_e32 v0, v0, v0
	v_fma_f32 v0, v0, s0, 0.5
	s_mov_b32 s0, 0xc1f00000
	v_sub_f32_e32 v2, v6, v7
	v_add_f32_e32 v0, v2, v0
	v_cmp_le_f32_e32 vcc, s0, v0
	s_and_b64 exec, exec, vcc
	s_cbranch_execz .LBB0_484
	s_ff1_i32_b64 s23, exec
	s_nop 0
	v_readlane_b32 s3, v194, s23
	v_mbcnt_lo_u32_b32 v0, exec_lo, 0
	v_mbcnt_hi_u32_b32 v0, exec_hi, v0
	v_cmp_eq_u32_e32 vcc, 0, v0
	s_and_saveexec_b64 s[0:1], vcc
	s_xor_b64 s[0:1], exec, s[0:1]
	v_mov_b32_e32 v0, s3
	ds_min_i32 v1, v0 offset:37376
